# merge EpiBranch epilogue: 16 serialized G/Y load round trips per unit replaced by 8-deep rolling window with counted vmcnt
# speedup vs baseline: 1.0432x; 1.0073x over previous
.LBB0_1278:
	v_lshlrev_b32_e32 v232, 4, v139
	v_add3_u32 v232, s60, v5, v232
	v_lshlrev_b32_e32 v232, 4, v232
	s_lshl_b32 s4, s8, 6
	s_lshl_b32 s5, s6, 4
	s_add_i32 s4, s4, s5
	s_lshl_b32 s4, s4, 13
	s_add_u32 s72, s58, s4
	s_addc_u32 s73, s59, 0
	s_cmp_eq_u32 s83, 0
	s_cbranch_scc1 .Lmrg_seg0
	s_cmpk_eq_i32 s83, 0x100
	s_cbranch_scc1 .Lmrg_seg1
	s_branch .Lmrg_seg2
.Lmrg_seg0:
	s_mov_b64 s[70:71], s[72:73]
	v_mov_b32_e32 v230, 0
	v_mov_b32_e32 v231, 0
	s_add_u32 s4, s70, 0x0
	s_addc_u32 s5, s71, 0
	global_load_dwordx4 v[130:133], v232, s[4:5]
	s_add_u32 s4, s70, 0x2000
	s_addc_u32 s5, s71, 0
	global_load_dwordx4 v[134:137], v232, s[4:5]
	s_add_u32 s4, s70, 0x4000
	s_addc_u32 s5, s71, 0
	global_load_dwordx4 v[156:159], v232, s[4:5]
	s_add_u32 s4, s70, 0x6000
	s_addc_u32 s5, s71, 0
	global_load_dwordx4 v[162:165], v232, s[4:5]
	s_add_u32 s4, s70, 0x8000
	s_addc_u32 s5, s71, 0
	global_load_dwordx4 v[166:169], v232, s[4:5]
	s_add_u32 s4, s70, 0xa000
	s_addc_u32 s5, s71, 0
	global_load_dwordx4 v[170:173], v232, s[4:5]
	s_add_u32 s4, s70, 0xc000
	s_addc_u32 s5, s71, 0
	global_load_dwordx4 v[174:177], v232, s[4:5]
	s_add_u32 s4, s70, 0xe000
	s_addc_u32 s5, s71, 0
	global_load_dwordx4 v[178:181], v232, s[4:5]
	s_waitcnt vmcnt(7)
	v_lshlrev_b32_e32 v224, 16, v130
	v_and_b32_e32 v225, 0xffff0000, v130
	v_pk_fma_f32 v[126:127], v[126:127], v[224:225], v[230:231]
	v_lshlrev_b32_e32 v226, 16, v131
	v_and_b32_e32 v227, 0xffff0000, v131
	v_pk_fma_f32 v[128:129], v[128:129], v[226:227], v[230:231]
	v_lshlrev_b32_e32 v224, 16, v132
	v_and_b32_e32 v225, 0xffff0000, v132
	v_pk_fma_f32 v[122:123], v[122:123], v[224:225], v[230:231]
	v_lshlrev_b32_e32 v226, 16, v133
	v_and_b32_e32 v227, 0xffff0000, v133
	v_pk_fma_f32 v[124:125], v[124:125], v[226:227], v[230:231]
	v_cvt_pk_bf16_f32 v126, v126, v127
	v_cvt_pk_bf16_f32 v127, v128, v129
	v_cvt_pk_bf16_f32 v128, v122, v123
	v_cvt_pk_bf16_f32 v129, v124, v125
	s_add_u32 s76, s72, 0x0
	s_addc_u32 s77, s73, 0
	global_store_dwordx4 v232, v[126:129], s[76:77]
	s_add_u32 s4, s70, 0x10000
	s_addc_u32 s5, s71, 0
	global_load_dwordx4 v[130:133], v232, s[4:5]
	s_waitcnt vmcnt(8)
	v_lshlrev_b32_e32 v224, 16, v134
	v_and_b32_e32 v225, 0xffff0000, v134
	v_pk_fma_f32 v[118:119], v[118:119], v[224:225], v[230:231]
	v_lshlrev_b32_e32 v226, 16, v135
	v_and_b32_e32 v227, 0xffff0000, v135
	v_pk_fma_f32 v[120:121], v[120:121], v[226:227], v[230:231]
	v_lshlrev_b32_e32 v224, 16, v136
	v_and_b32_e32 v225, 0xffff0000, v136
	v_pk_fma_f32 v[114:115], v[114:115], v[224:225], v[230:231]
	v_lshlrev_b32_e32 v226, 16, v137
	v_and_b32_e32 v227, 0xffff0000, v137
	v_pk_fma_f32 v[116:117], v[116:117], v[226:227], v[230:231]
	v_cvt_pk_bf16_f32 v118, v118, v119
	v_cvt_pk_bf16_f32 v119, v120, v121
	v_cvt_pk_bf16_f32 v120, v114, v115
	v_cvt_pk_bf16_f32 v121, v116, v117
	s_add_u32 s76, s72, 0x2000
	s_addc_u32 s77, s73, 0
	global_store_dwordx4 v232, v[118:121], s[76:77]
	s_add_u32 s4, s70, 0x12000
	s_addc_u32 s5, s71, 0
	global_load_dwordx4 v[134:137], v232, s[4:5]
	s_waitcnt vmcnt(9)
	v_lshlrev_b32_e32 v224, 16, v156
	v_and_b32_e32 v225, 0xffff0000, v156
	v_pk_fma_f32 v[110:111], v[110:111], v[224:225], v[230:231]
	v_lshlrev_b32_e32 v226, 16, v157
	v_and_b32_e32 v227, 0xffff0000, v157
	v_pk_fma_f32 v[112:113], v[112:113], v[226:227], v[230:231]
	v_lshlrev_b32_e32 v224, 16, v158
	v_and_b32_e32 v225, 0xffff0000, v158
	v_pk_fma_f32 v[106:107], v[106:107], v[224:225], v[230:231]
	v_lshlrev_b32_e32 v226, 16, v159
	v_and_b32_e32 v227, 0xffff0000, v159
	v_pk_fma_f32 v[108:109], v[108:109], v[226:227], v[230:231]
	v_cvt_pk_bf16_f32 v110, v110, v111
	v_cvt_pk_bf16_f32 v111, v112, v113
	v_cvt_pk_bf16_f32 v112, v106, v107
	v_cvt_pk_bf16_f32 v113, v108, v109
	s_add_u32 s76, s72, 0x4000
	s_addc_u32 s77, s73, 0
	global_store_dwordx4 v232, v[110:113], s[76:77]
	s_add_u32 s4, s70, 0x14000
	s_addc_u32 s5, s71, 0
	global_load_dwordx4 v[156:159], v232, s[4:5]
	s_waitcnt vmcnt(10)
	v_lshlrev_b32_e32 v224, 16, v162
	v_and_b32_e32 v225, 0xffff0000, v162
	v_pk_fma_f32 v[102:103], v[102:103], v[224:225], v[230:231]
	v_lshlrev_b32_e32 v226, 16, v163
	v_and_b32_e32 v227, 0xffff0000, v163
	v_pk_fma_f32 v[104:105], v[104:105], v[226:227], v[230:231]
	v_lshlrev_b32_e32 v224, 16, v164
	v_and_b32_e32 v225, 0xffff0000, v164
	v_pk_fma_f32 v[98:99], v[98:99], v[224:225], v[230:231]
	v_lshlrev_b32_e32 v226, 16, v165
	v_and_b32_e32 v227, 0xffff0000, v165
	v_pk_fma_f32 v[100:101], v[100:101], v[226:227], v[230:231]
	v_cvt_pk_bf16_f32 v102, v102, v103
	v_cvt_pk_bf16_f32 v103, v104, v105
	v_cvt_pk_bf16_f32 v104, v98, v99
	v_cvt_pk_bf16_f32 v105, v100, v101
	s_add_u32 s76, s72, 0x6000
	s_addc_u32 s77, s73, 0
	global_store_dwordx4 v232, v[102:105], s[76:77]
	s_add_u32 s4, s70, 0x16000
	s_addc_u32 s5, s71, 0
	global_load_dwordx4 v[162:165], v232, s[4:5]
	s_waitcnt vmcnt(11)
	v_lshlrev_b32_e32 v224, 16, v166
	v_and_b32_e32 v225, 0xffff0000, v166
	v_pk_fma_f32 v[94:95], v[94:95], v[224:225], v[230:231]
	v_lshlrev_b32_e32 v226, 16, v167
	v_and_b32_e32 v227, 0xffff0000, v167
	v_pk_fma_f32 v[96:97], v[96:97], v[226:227], v[230:231]
	v_lshlrev_b32_e32 v224, 16, v168
	v_and_b32_e32 v225, 0xffff0000, v168
	v_pk_fma_f32 v[90:91], v[90:91], v[224:225], v[230:231]
	v_lshlrev_b32_e32 v226, 16, v169
	v_and_b32_e32 v227, 0xffff0000, v169
	v_pk_fma_f32 v[92:93], v[92:93], v[226:227], v[230:231]
	v_cvt_pk_bf16_f32 v94, v94, v95
	v_cvt_pk_bf16_f32 v95, v96, v97
	v_cvt_pk_bf16_f32 v96, v90, v91
	v_cvt_pk_bf16_f32 v97, v92, v93
	s_add_u32 s76, s72, 0x8000
	s_addc_u32 s77, s73, 0
	global_store_dwordx4 v232, v[94:97], s[76:77]
	s_add_u32 s4, s70, 0x18000
	s_addc_u32 s5, s71, 0
	global_load_dwordx4 v[166:169], v232, s[4:5]
	s_waitcnt vmcnt(12)
	v_lshlrev_b32_e32 v224, 16, v170
	v_and_b32_e32 v225, 0xffff0000, v170
	v_pk_fma_f32 v[86:87], v[86:87], v[224:225], v[230:231]
	v_lshlrev_b32_e32 v226, 16, v171
	v_and_b32_e32 v227, 0xffff0000, v171
	v_pk_fma_f32 v[88:89], v[88:89], v[226:227], v[230:231]
	v_lshlrev_b32_e32 v224, 16, v172
	v_and_b32_e32 v225, 0xffff0000, v172
	v_pk_fma_f32 v[82:83], v[82:83], v[224:225], v[230:231]
	v_lshlrev_b32_e32 v226, 16, v173
	v_and_b32_e32 v227, 0xffff0000, v173
	v_pk_fma_f32 v[84:85], v[84:85], v[226:227], v[230:231]
	v_cvt_pk_bf16_f32 v86, v86, v87
	v_cvt_pk_bf16_f32 v87, v88, v89
	v_cvt_pk_bf16_f32 v88, v82, v83
	v_cvt_pk_bf16_f32 v89, v84, v85
	s_add_u32 s76, s72, 0xa000
	s_addc_u32 s77, s73, 0
	global_store_dwordx4 v232, v[86:89], s[76:77]
	s_add_u32 s4, s70, 0x1a000
	s_addc_u32 s5, s71, 0
	global_load_dwordx4 v[170:173], v232, s[4:5]
	s_waitcnt vmcnt(13)
	v_lshlrev_b32_e32 v224, 16, v174
	v_and_b32_e32 v225, 0xffff0000, v174
	v_pk_fma_f32 v[78:79], v[78:79], v[224:225], v[230:231]
	v_lshlrev_b32_e32 v226, 16, v175
	v_and_b32_e32 v227, 0xffff0000, v175
	v_pk_fma_f32 v[80:81], v[80:81], v[226:227], v[230:231]
	v_lshlrev_b32_e32 v224, 16, v176
	v_and_b32_e32 v225, 0xffff0000, v176
	v_pk_fma_f32 v[74:75], v[74:75], v[224:225], v[230:231]
	v_lshlrev_b32_e32 v226, 16, v177
	v_and_b32_e32 v227, 0xffff0000, v177
	v_pk_fma_f32 v[76:77], v[76:77], v[226:227], v[230:231]
	v_cvt_pk_bf16_f32 v78, v78, v79
	v_cvt_pk_bf16_f32 v79, v80, v81
	v_cvt_pk_bf16_f32 v80, v74, v75
	v_cvt_pk_bf16_f32 v81, v76, v77
	s_add_u32 s76, s72, 0xc000
	s_addc_u32 s77, s73, 0
	global_store_dwordx4 v232, v[78:81], s[76:77]
	s_add_u32 s4, s70, 0x1c000
	s_addc_u32 s5, s71, 0
	global_load_dwordx4 v[174:177], v232, s[4:5]
	s_waitcnt vmcnt(14)
	v_lshlrev_b32_e32 v224, 16, v178
	v_and_b32_e32 v225, 0xffff0000, v178
	v_pk_fma_f32 v[70:71], v[70:71], v[224:225], v[230:231]
	v_lshlrev_b32_e32 v226, 16, v179
	v_and_b32_e32 v227, 0xffff0000, v179
	v_pk_fma_f32 v[72:73], v[72:73], v[226:227], v[230:231]
	v_lshlrev_b32_e32 v224, 16, v180
	v_and_b32_e32 v225, 0xffff0000, v180
	v_pk_fma_f32 v[66:67], v[66:67], v[224:225], v[230:231]
	v_lshlrev_b32_e32 v226, 16, v181
	v_and_b32_e32 v227, 0xffff0000, v181
	v_pk_fma_f32 v[68:69], v[68:69], v[226:227], v[230:231]
	v_cvt_pk_bf16_f32 v70, v70, v71
	v_cvt_pk_bf16_f32 v71, v72, v73
	v_cvt_pk_bf16_f32 v72, v66, v67
	v_cvt_pk_bf16_f32 v73, v68, v69
	s_add_u32 s76, s72, 0xe000
	s_addc_u32 s77, s73, 0
	global_store_dwordx4 v232, v[70:73], s[76:77]
	s_add_u32 s4, s70, 0x1e000
	s_addc_u32 s5, s71, 0
	global_load_dwordx4 v[178:181], v232, s[4:5]
	s_waitcnt vmcnt(14)
	v_lshlrev_b32_e32 v224, 16, v130
	v_and_b32_e32 v225, 0xffff0000, v130
	v_pk_fma_f32 v[62:63], v[62:63], v[224:225], v[230:231]
	v_lshlrev_b32_e32 v226, 16, v131
	v_and_b32_e32 v227, 0xffff0000, v131
	v_pk_fma_f32 v[64:65], v[64:65], v[226:227], v[230:231]
	v_lshlrev_b32_e32 v224, 16, v132
	v_and_b32_e32 v225, 0xffff0000, v132
	v_pk_fma_f32 v[58:59], v[58:59], v[224:225], v[230:231]
	v_lshlrev_b32_e32 v226, 16, v133
	v_and_b32_e32 v227, 0xffff0000, v133
	v_pk_fma_f32 v[60:61], v[60:61], v[226:227], v[230:231]
	v_cvt_pk_bf16_f32 v62, v62, v63
	v_cvt_pk_bf16_f32 v63, v64, v65
	v_cvt_pk_bf16_f32 v64, v58, v59
	v_cvt_pk_bf16_f32 v65, v60, v61
	s_add_u32 s76, s72, 0x10000
	s_addc_u32 s77, s73, 0
	global_store_dwordx4 v232, v[62:65], s[76:77]
	s_waitcnt vmcnt(13)
	v_lshlrev_b32_e32 v224, 16, v134
	v_and_b32_e32 v225, 0xffff0000, v134
	v_pk_fma_f32 v[54:55], v[54:55], v[224:225], v[230:231]
	v_lshlrev_b32_e32 v226, 16, v135
	v_and_b32_e32 v227, 0xffff0000, v135
	v_pk_fma_f32 v[56:57], v[56:57], v[226:227], v[230:231]
	v_lshlrev_b32_e32 v224, 16, v136
	v_and_b32_e32 v225, 0xffff0000, v136
	v_pk_fma_f32 v[50:51], v[50:51], v[224:225], v[230:231]
	v_lshlrev_b32_e32 v226, 16, v137
	v_and_b32_e32 v227, 0xffff0000, v137
	v_pk_fma_f32 v[52:53], v[52:53], v[226:227], v[230:231]
	v_cvt_pk_bf16_f32 v54, v54, v55
	v_cvt_pk_bf16_f32 v55, v56, v57
	v_cvt_pk_bf16_f32 v56, v50, v51
	v_cvt_pk_bf16_f32 v57, v52, v53
	s_add_u32 s76, s72, 0x12000
	s_addc_u32 s77, s73, 0
	global_store_dwordx4 v232, v[54:57], s[76:77]
	s_waitcnt vmcnt(12)
	v_lshlrev_b32_e32 v224, 16, v156
	v_and_b32_e32 v225, 0xffff0000, v156
	v_pk_fma_f32 v[46:47], v[46:47], v[224:225], v[230:231]
	v_lshlrev_b32_e32 v226, 16, v157
	v_and_b32_e32 v227, 0xffff0000, v157
	v_pk_fma_f32 v[48:49], v[48:49], v[226:227], v[230:231]
	v_lshlrev_b32_e32 v224, 16, v158
	v_and_b32_e32 v225, 0xffff0000, v158
	v_pk_fma_f32 v[42:43], v[42:43], v[224:225], v[230:231]
	v_lshlrev_b32_e32 v226, 16, v159
	v_and_b32_e32 v227, 0xffff0000, v159
	v_pk_fma_f32 v[44:45], v[44:45], v[226:227], v[230:231]
	v_cvt_pk_bf16_f32 v46, v46, v47
	v_cvt_pk_bf16_f32 v47, v48, v49
	v_cvt_pk_bf16_f32 v48, v42, v43
	v_cvt_pk_bf16_f32 v49, v44, v45
	s_add_u32 s76, s72, 0x14000
	s_addc_u32 s77, s73, 0
	global_store_dwordx4 v232, v[46:49], s[76:77]
	s_waitcnt vmcnt(11)
	v_lshlrev_b32_e32 v224, 16, v162
	v_and_b32_e32 v225, 0xffff0000, v162
	v_pk_fma_f32 v[38:39], v[38:39], v[224:225], v[230:231]
	v_lshlrev_b32_e32 v226, 16, v163
	v_and_b32_e32 v227, 0xffff0000, v163
	v_pk_fma_f32 v[40:41], v[40:41], v[226:227], v[230:231]
	v_lshlrev_b32_e32 v224, 16, v164
	v_and_b32_e32 v225, 0xffff0000, v164
	v_pk_fma_f32 v[34:35], v[34:35], v[224:225], v[230:231]
	v_lshlrev_b32_e32 v226, 16, v165
	v_and_b32_e32 v227, 0xffff0000, v165
	v_pk_fma_f32 v[36:37], v[36:37], v[226:227], v[230:231]
	v_cvt_pk_bf16_f32 v38, v38, v39
	v_cvt_pk_bf16_f32 v39, v40, v41
	v_cvt_pk_bf16_f32 v40, v34, v35
	v_cvt_pk_bf16_f32 v41, v36, v37
	s_add_u32 s76, s72, 0x16000
	s_addc_u32 s77, s73, 0
	global_store_dwordx4 v232, v[38:41], s[76:77]
	s_waitcnt vmcnt(10)
	v_lshlrev_b32_e32 v224, 16, v166
	v_and_b32_e32 v225, 0xffff0000, v166
	v_pk_fma_f32 v[30:31], v[30:31], v[224:225], v[230:231]
	v_lshlrev_b32_e32 v226, 16, v167
	v_and_b32_e32 v227, 0xffff0000, v167
	v_pk_fma_f32 v[32:33], v[32:33], v[226:227], v[230:231]
	v_lshlrev_b32_e32 v224, 16, v168
	v_and_b32_e32 v225, 0xffff0000, v168
	v_pk_fma_f32 v[26:27], v[26:27], v[224:225], v[230:231]
	v_lshlrev_b32_e32 v226, 16, v169
	v_and_b32_e32 v227, 0xffff0000, v169
	v_pk_fma_f32 v[28:29], v[28:29], v[226:227], v[230:231]
	v_cvt_pk_bf16_f32 v30, v30, v31
	v_cvt_pk_bf16_f32 v31, v32, v33
	v_cvt_pk_bf16_f32 v32, v26, v27
	v_cvt_pk_bf16_f32 v33, v28, v29
	s_add_u32 s76, s72, 0x18000
	s_addc_u32 s77, s73, 0
	global_store_dwordx4 v232, v[30:33], s[76:77]
	s_waitcnt vmcnt(9)
	v_lshlrev_b32_e32 v224, 16, v170
	v_and_b32_e32 v225, 0xffff0000, v170
	v_pk_fma_f32 v[22:23], v[22:23], v[224:225], v[230:231]
	v_lshlrev_b32_e32 v226, 16, v171
	v_and_b32_e32 v227, 0xffff0000, v171
	v_pk_fma_f32 v[24:25], v[24:25], v[226:227], v[230:231]
	v_lshlrev_b32_e32 v224, 16, v172
	v_and_b32_e32 v225, 0xffff0000, v172
	v_pk_fma_f32 v[18:19], v[18:19], v[224:225], v[230:231]
	v_lshlrev_b32_e32 v226, 16, v173
	v_and_b32_e32 v227, 0xffff0000, v173
	v_pk_fma_f32 v[20:21], v[20:21], v[226:227], v[230:231]
	v_cvt_pk_bf16_f32 v22, v22, v23
	v_cvt_pk_bf16_f32 v23, v24, v25
	v_cvt_pk_bf16_f32 v24, v18, v19
	v_cvt_pk_bf16_f32 v25, v20, v21
	s_add_u32 s76, s72, 0x1a000
	s_addc_u32 s77, s73, 0
	global_store_dwordx4 v232, v[22:25], s[76:77]
	s_waitcnt vmcnt(8)
	v_lshlrev_b32_e32 v224, 16, v174
	v_and_b32_e32 v225, 0xffff0000, v174
	v_pk_fma_f32 v[14:15], v[14:15], v[224:225], v[230:231]
	v_lshlrev_b32_e32 v226, 16, v175
	v_and_b32_e32 v227, 0xffff0000, v175
	v_pk_fma_f32 v[16:17], v[16:17], v[226:227], v[230:231]
	v_lshlrev_b32_e32 v224, 16, v176
	v_and_b32_e32 v225, 0xffff0000, v176
	v_pk_fma_f32 v[10:11], v[10:11], v[224:225], v[230:231]
	v_lshlrev_b32_e32 v226, 16, v177
	v_and_b32_e32 v227, 0xffff0000, v177
	v_pk_fma_f32 v[12:13], v[12:13], v[226:227], v[230:231]
	v_cvt_pk_bf16_f32 v14, v14, v15
	v_cvt_pk_bf16_f32 v15, v16, v17
	v_cvt_pk_bf16_f32 v16, v10, v11
	v_cvt_pk_bf16_f32 v17, v12, v13
	s_add_u32 s76, s72, 0x1c000
	s_addc_u32 s77, s73, 0
	global_store_dwordx4 v232, v[14:17], s[76:77]
	s_waitcnt vmcnt(7)
	v_lshlrev_b32_e32 v224, 16, v178
	v_and_b32_e32 v225, 0xffff0000, v178
	v_pk_fma_f32 v[6:7], v[6:7], v[224:225], v[230:231]
	v_lshlrev_b32_e32 v226, 16, v179
	v_and_b32_e32 v227, 0xffff0000, v179
	v_pk_fma_f32 v[8:9], v[8:9], v[226:227], v[230:231]
	v_lshlrev_b32_e32 v224, 16, v180
	v_and_b32_e32 v225, 0xffff0000, v180
	v_pk_fma_f32 v[0:1], v[0:1], v[224:225], v[230:231]
	v_lshlrev_b32_e32 v226, 16, v181
	v_and_b32_e32 v227, 0xffff0000, v181
	v_pk_fma_f32 v[2:3], v[2:3], v[226:227], v[230:231]
	v_cvt_pk_bf16_f32 v6, v6, v7
	v_cvt_pk_bf16_f32 v7, v8, v9
	v_cvt_pk_bf16_f32 v8, v0, v1
	v_cvt_pk_bf16_f32 v9, v2, v3
	s_add_u32 s76, s72, 0x1e000
	s_addc_u32 s77, s73, 0
	global_store_dwordx4 v232, v[6:9], s[76:77]
	s_branch .Lmrg_done
.Lmrg_seg1:
	s_add_u32 s70, s26, 0x4512000
	s_addc_u32 s71, s27, 0
	s_add_u32 s70, s70, s4
	s_addc_u32 s71, s71, 0
	s_add_u32 s4, s70, 0x0
	s_addc_u32 s5, s71, 0
	global_load_dwordx4 v[130:133], v232, s[4:5]
	s_add_u32 s4, s72, 0x0
	s_addc_u32 s5, s73, 0
	global_load_dwordx4 v[182:185], v232, s[4:5]
	s_add_u32 s4, s70, 0x2000
	s_addc_u32 s5, s71, 0
	global_load_dwordx4 v[134:137], v232, s[4:5]
	s_add_u32 s4, s72, 0x2000
	s_addc_u32 s5, s73, 0
	global_load_dwordx4 v[186:189], v232, s[4:5]
	s_add_u32 s4, s70, 0x4000
	s_addc_u32 s5, s71, 0
	global_load_dwordx4 v[156:159], v232, s[4:5]
	s_add_u32 s4, s72, 0x4000
	s_addc_u32 s5, s73, 0
	global_load_dwordx4 v[190:193], v232, s[4:5]
	s_add_u32 s4, s70, 0x6000
	s_addc_u32 s5, s71, 0
	global_load_dwordx4 v[162:165], v232, s[4:5]
	s_add_u32 s4, s72, 0x6000
	s_addc_u32 s5, s73, 0
	global_load_dwordx4 v[194:197], v232, s[4:5]
	s_add_u32 s4, s70, 0x8000
	s_addc_u32 s5, s71, 0
	global_load_dwordx4 v[166:169], v232, s[4:5]
	s_add_u32 s4, s72, 0x8000
	s_addc_u32 s5, s73, 0
	global_load_dwordx4 v[198:201], v232, s[4:5]
	s_add_u32 s4, s70, 0xa000
	s_addc_u32 s5, s71, 0
	global_load_dwordx4 v[170:173], v232, s[4:5]
	s_add_u32 s4, s72, 0xa000
	s_addc_u32 s5, s73, 0
	global_load_dwordx4 v[202:205], v232, s[4:5]
	s_add_u32 s4, s70, 0xc000
	s_addc_u32 s5, s71, 0
	global_load_dwordx4 v[174:177], v232, s[4:5]
	s_add_u32 s4, s72, 0xc000
	s_addc_u32 s5, s73, 0
	global_load_dwordx4 v[206:209], v232, s[4:5]
	s_add_u32 s4, s70, 0xe000
	s_addc_u32 s5, s71, 0
	global_load_dwordx4 v[178:181], v232, s[4:5]
	s_add_u32 s4, s72, 0xe000
	s_addc_u32 s5, s73, 0
	global_load_dwordx4 v[210:213], v232, s[4:5]
	s_waitcnt vmcnt(14)
	v_lshlrev_b32_e32 v224, 16, v130
	v_and_b32_e32 v225, 0xffff0000, v130
	v_lshlrev_b32_e32 v228, 16, v182
	v_and_b32_e32 v229, 0xffff0000, v182
	v_pk_fma_f32 v[126:127], v[126:127], v[224:225], v[228:229]
	v_lshlrev_b32_e32 v226, 16, v131
	v_and_b32_e32 v227, 0xffff0000, v131
	v_lshlrev_b32_e32 v230, 16, v183
	v_and_b32_e32 v231, 0xffff0000, v183
	v_pk_fma_f32 v[128:129], v[128:129], v[226:227], v[230:231]
	v_lshlrev_b32_e32 v224, 16, v132
	v_and_b32_e32 v225, 0xffff0000, v132
	v_lshlrev_b32_e32 v228, 16, v184
	v_and_b32_e32 v229, 0xffff0000, v184
	v_pk_fma_f32 v[122:123], v[122:123], v[224:225], v[228:229]
	v_lshlrev_b32_e32 v226, 16, v133
	v_and_b32_e32 v227, 0xffff0000, v133
	v_lshlrev_b32_e32 v230, 16, v185
	v_and_b32_e32 v231, 0xffff0000, v185
	v_pk_fma_f32 v[124:125], v[124:125], v[226:227], v[230:231]
	v_cvt_pk_bf16_f32 v126, v126, v127
	v_cvt_pk_bf16_f32 v127, v128, v129
	v_cvt_pk_bf16_f32 v128, v122, v123
	v_cvt_pk_bf16_f32 v129, v124, v125
	s_add_u32 s76, s72, 0x0
	s_addc_u32 s77, s73, 0
	global_store_dwordx4 v232, v[126:129], s[76:77]
	s_add_u32 s4, s70, 0x10000
	s_addc_u32 s5, s71, 0
	global_load_dwordx4 v[130:133], v232, s[4:5]
	s_add_u32 s4, s72, 0x10000
	s_addc_u32 s5, s73, 0
	global_load_dwordx4 v[182:185], v232, s[4:5]
	s_waitcnt vmcnt(15)
	v_lshlrev_b32_e32 v224, 16, v134
	v_and_b32_e32 v225, 0xffff0000, v134
	v_lshlrev_b32_e32 v228, 16, v186
	v_and_b32_e32 v229, 0xffff0000, v186
	v_pk_fma_f32 v[118:119], v[118:119], v[224:225], v[228:229]
	v_lshlrev_b32_e32 v226, 16, v135
	v_and_b32_e32 v227, 0xffff0000, v135
	v_lshlrev_b32_e32 v230, 16, v187
	v_and_b32_e32 v231, 0xffff0000, v187
	v_pk_fma_f32 v[120:121], v[120:121], v[226:227], v[230:231]
	v_lshlrev_b32_e32 v224, 16, v136
	v_and_b32_e32 v225, 0xffff0000, v136
	v_lshlrev_b32_e32 v228, 16, v188
	v_and_b32_e32 v229, 0xffff0000, v188
	v_pk_fma_f32 v[114:115], v[114:115], v[224:225], v[228:229]
	v_lshlrev_b32_e32 v226, 16, v137
	v_and_b32_e32 v227, 0xffff0000, v137
	v_lshlrev_b32_e32 v230, 16, v189
	v_and_b32_e32 v231, 0xffff0000, v189
	v_pk_fma_f32 v[116:117], v[116:117], v[226:227], v[230:231]
	v_cvt_pk_bf16_f32 v118, v118, v119
	v_cvt_pk_bf16_f32 v119, v120, v121
	v_cvt_pk_bf16_f32 v120, v114, v115
	v_cvt_pk_bf16_f32 v121, v116, v117
	s_add_u32 s76, s72, 0x2000
	s_addc_u32 s77, s73, 0
	global_store_dwordx4 v232, v[118:121], s[76:77]
	s_add_u32 s4, s70, 0x12000
	s_addc_u32 s5, s71, 0
	global_load_dwordx4 v[134:137], v232, s[4:5]
	s_add_u32 s4, s72, 0x12000
	s_addc_u32 s5, s73, 0
	global_load_dwordx4 v[186:189], v232, s[4:5]
	s_waitcnt vmcnt(16)
	v_lshlrev_b32_e32 v224, 16, v156
	v_and_b32_e32 v225, 0xffff0000, v156
	v_lshlrev_b32_e32 v228, 16, v190
	v_and_b32_e32 v229, 0xffff0000, v190
	v_pk_fma_f32 v[110:111], v[110:111], v[224:225], v[228:229]
	v_lshlrev_b32_e32 v226, 16, v157
	v_and_b32_e32 v227, 0xffff0000, v157
	v_lshlrev_b32_e32 v230, 16, v191
	v_and_b32_e32 v231, 0xffff0000, v191
	v_pk_fma_f32 v[112:113], v[112:113], v[226:227], v[230:231]
	v_lshlrev_b32_e32 v224, 16, v158
	v_and_b32_e32 v225, 0xffff0000, v158
	v_lshlrev_b32_e32 v228, 16, v192
	v_and_b32_e32 v229, 0xffff0000, v192
	v_pk_fma_f32 v[106:107], v[106:107], v[224:225], v[228:229]
	v_lshlrev_b32_e32 v226, 16, v159
	v_and_b32_e32 v227, 0xffff0000, v159
	v_lshlrev_b32_e32 v230, 16, v193
	v_and_b32_e32 v231, 0xffff0000, v193
	v_pk_fma_f32 v[108:109], v[108:109], v[226:227], v[230:231]
	v_cvt_pk_bf16_f32 v110, v110, v111
	v_cvt_pk_bf16_f32 v111, v112, v113
	v_cvt_pk_bf16_f32 v112, v106, v107
	v_cvt_pk_bf16_f32 v113, v108, v109
	s_add_u32 s76, s72, 0x4000
	s_addc_u32 s77, s73, 0
	global_store_dwordx4 v232, v[110:113], s[76:77]
	s_add_u32 s4, s70, 0x14000
	s_addc_u32 s5, s71, 0
	global_load_dwordx4 v[156:159], v232, s[4:5]
	s_add_u32 s4, s72, 0x14000
	s_addc_u32 s5, s73, 0
	global_load_dwordx4 v[190:193], v232, s[4:5]
	s_waitcnt vmcnt(17)
	v_lshlrev_b32_e32 v224, 16, v162
	v_and_b32_e32 v225, 0xffff0000, v162
	v_lshlrev_b32_e32 v228, 16, v194
	v_and_b32_e32 v229, 0xffff0000, v194
	v_pk_fma_f32 v[102:103], v[102:103], v[224:225], v[228:229]
	v_lshlrev_b32_e32 v226, 16, v163
	v_and_b32_e32 v227, 0xffff0000, v163
	v_lshlrev_b32_e32 v230, 16, v195
	v_and_b32_e32 v231, 0xffff0000, v195
	v_pk_fma_f32 v[104:105], v[104:105], v[226:227], v[230:231]
	v_lshlrev_b32_e32 v224, 16, v164
	v_and_b32_e32 v225, 0xffff0000, v164
	v_lshlrev_b32_e32 v228, 16, v196
	v_and_b32_e32 v229, 0xffff0000, v196
	v_pk_fma_f32 v[98:99], v[98:99], v[224:225], v[228:229]
	v_lshlrev_b32_e32 v226, 16, v165
	v_and_b32_e32 v227, 0xffff0000, v165
	v_lshlrev_b32_e32 v230, 16, v197
	v_and_b32_e32 v231, 0xffff0000, v197
	v_pk_fma_f32 v[100:101], v[100:101], v[226:227], v[230:231]
	v_cvt_pk_bf16_f32 v102, v102, v103
	v_cvt_pk_bf16_f32 v103, v104, v105
	v_cvt_pk_bf16_f32 v104, v98, v99
	v_cvt_pk_bf16_f32 v105, v100, v101
	s_add_u32 s76, s72, 0x6000
	s_addc_u32 s77, s73, 0
	global_store_dwordx4 v232, v[102:105], s[76:77]
	s_add_u32 s4, s70, 0x16000
	s_addc_u32 s5, s71, 0
	global_load_dwordx4 v[162:165], v232, s[4:5]
	s_add_u32 s4, s72, 0x16000
	s_addc_u32 s5, s73, 0
	global_load_dwordx4 v[194:197], v232, s[4:5]
	s_waitcnt vmcnt(18)
	v_lshlrev_b32_e32 v224, 16, v166
	v_and_b32_e32 v225, 0xffff0000, v166
	v_lshlrev_b32_e32 v228, 16, v198
	v_and_b32_e32 v229, 0xffff0000, v198
	v_pk_fma_f32 v[94:95], v[94:95], v[224:225], v[228:229]
	v_lshlrev_b32_e32 v226, 16, v167
	v_and_b32_e32 v227, 0xffff0000, v167
	v_lshlrev_b32_e32 v230, 16, v199
	v_and_b32_e32 v231, 0xffff0000, v199
	v_pk_fma_f32 v[96:97], v[96:97], v[226:227], v[230:231]
	v_lshlrev_b32_e32 v224, 16, v168
	v_and_b32_e32 v225, 0xffff0000, v168
	v_lshlrev_b32_e32 v228, 16, v200
	v_and_b32_e32 v229, 0xffff0000, v200
	v_pk_fma_f32 v[90:91], v[90:91], v[224:225], v[228:229]
	v_lshlrev_b32_e32 v226, 16, v169
	v_and_b32_e32 v227, 0xffff0000, v169
	v_lshlrev_b32_e32 v230, 16, v201
	v_and_b32_e32 v231, 0xffff0000, v201
	v_pk_fma_f32 v[92:93], v[92:93], v[226:227], v[230:231]
	v_cvt_pk_bf16_f32 v94, v94, v95
	v_cvt_pk_bf16_f32 v95, v96, v97
	v_cvt_pk_bf16_f32 v96, v90, v91
	v_cvt_pk_bf16_f32 v97, v92, v93
	s_add_u32 s76, s72, 0x8000
	s_addc_u32 s77, s73, 0
	global_store_dwordx4 v232, v[94:97], s[76:77]
	s_add_u32 s4, s70, 0x18000
	s_addc_u32 s5, s71, 0
	global_load_dwordx4 v[166:169], v232, s[4:5]
	s_add_u32 s4, s72, 0x18000
	s_addc_u32 s5, s73, 0
	global_load_dwordx4 v[198:201], v232, s[4:5]
	s_waitcnt vmcnt(19)
	v_lshlrev_b32_e32 v224, 16, v170
	v_and_b32_e32 v225, 0xffff0000, v170
	v_lshlrev_b32_e32 v228, 16, v202
	v_and_b32_e32 v229, 0xffff0000, v202
	v_pk_fma_f32 v[86:87], v[86:87], v[224:225], v[228:229]
	v_lshlrev_b32_e32 v226, 16, v171
	v_and_b32_e32 v227, 0xffff0000, v171
	v_lshlrev_b32_e32 v230, 16, v203
	v_and_b32_e32 v231, 0xffff0000, v203
	v_pk_fma_f32 v[88:89], v[88:89], v[226:227], v[230:231]
	v_lshlrev_b32_e32 v224, 16, v172
	v_and_b32_e32 v225, 0xffff0000, v172
	v_lshlrev_b32_e32 v228, 16, v204
	v_and_b32_e32 v229, 0xffff0000, v204
	v_pk_fma_f32 v[82:83], v[82:83], v[224:225], v[228:229]
	v_lshlrev_b32_e32 v226, 16, v173
	v_and_b32_e32 v227, 0xffff0000, v173
	v_lshlrev_b32_e32 v230, 16, v205
	v_and_b32_e32 v231, 0xffff0000, v205
	v_pk_fma_f32 v[84:85], v[84:85], v[226:227], v[230:231]
	v_cvt_pk_bf16_f32 v86, v86, v87
	v_cvt_pk_bf16_f32 v87, v88, v89
	v_cvt_pk_bf16_f32 v88, v82, v83
	v_cvt_pk_bf16_f32 v89, v84, v85
	s_add_u32 s76, s72, 0xa000
	s_addc_u32 s77, s73, 0
	global_store_dwordx4 v232, v[86:89], s[76:77]
	s_add_u32 s4, s70, 0x1a000
	s_addc_u32 s5, s71, 0
	global_load_dwordx4 v[170:173], v232, s[4:5]
	s_add_u32 s4, s72, 0x1a000
	s_addc_u32 s5, s73, 0
	global_load_dwordx4 v[202:205], v232, s[4:5]
	s_waitcnt vmcnt(20)
	v_lshlrev_b32_e32 v224, 16, v174
	v_and_b32_e32 v225, 0xffff0000, v174
	v_lshlrev_b32_e32 v228, 16, v206
	v_and_b32_e32 v229, 0xffff0000, v206
	v_pk_fma_f32 v[78:79], v[78:79], v[224:225], v[228:229]
	v_lshlrev_b32_e32 v226, 16, v175
	v_and_b32_e32 v227, 0xffff0000, v175
	v_lshlrev_b32_e32 v230, 16, v207
	v_and_b32_e32 v231, 0xffff0000, v207
	v_pk_fma_f32 v[80:81], v[80:81], v[226:227], v[230:231]
	v_lshlrev_b32_e32 v224, 16, v176
	v_and_b32_e32 v225, 0xffff0000, v176
	v_lshlrev_b32_e32 v228, 16, v208
	v_and_b32_e32 v229, 0xffff0000, v208
	v_pk_fma_f32 v[74:75], v[74:75], v[224:225], v[228:229]
	v_lshlrev_b32_e32 v226, 16, v177
	v_and_b32_e32 v227, 0xffff0000, v177
	v_lshlrev_b32_e32 v230, 16, v209
	v_and_b32_e32 v231, 0xffff0000, v209
	v_pk_fma_f32 v[76:77], v[76:77], v[226:227], v[230:231]
	v_cvt_pk_bf16_f32 v78, v78, v79
	v_cvt_pk_bf16_f32 v79, v80, v81
	v_cvt_pk_bf16_f32 v80, v74, v75
	v_cvt_pk_bf16_f32 v81, v76, v77
	s_add_u32 s76, s72, 0xc000
	s_addc_u32 s77, s73, 0
	global_store_dwordx4 v232, v[78:81], s[76:77]
	s_add_u32 s4, s70, 0x1c000
	s_addc_u32 s5, s71, 0
	global_load_dwordx4 v[174:177], v232, s[4:5]
	s_add_u32 s4, s72, 0x1c000
	s_addc_u32 s5, s73, 0
	global_load_dwordx4 v[206:209], v232, s[4:5]
	s_waitcnt vmcnt(21)
	v_lshlrev_b32_e32 v224, 16, v178
	v_and_b32_e32 v225, 0xffff0000, v178
	v_lshlrev_b32_e32 v228, 16, v210
	v_and_b32_e32 v229, 0xffff0000, v210
	v_pk_fma_f32 v[70:71], v[70:71], v[224:225], v[228:229]
	v_lshlrev_b32_e32 v226, 16, v179
	v_and_b32_e32 v227, 0xffff0000, v179
	v_lshlrev_b32_e32 v230, 16, v211
	v_and_b32_e32 v231, 0xffff0000, v211
	v_pk_fma_f32 v[72:73], v[72:73], v[226:227], v[230:231]
	v_lshlrev_b32_e32 v224, 16, v180
	v_and_b32_e32 v225, 0xffff0000, v180
	v_lshlrev_b32_e32 v228, 16, v212
	v_and_b32_e32 v229, 0xffff0000, v212
	v_pk_fma_f32 v[66:67], v[66:67], v[224:225], v[228:229]
	v_lshlrev_b32_e32 v226, 16, v181
	v_and_b32_e32 v227, 0xffff0000, v181
	v_lshlrev_b32_e32 v230, 16, v213
	v_and_b32_e32 v231, 0xffff0000, v213
	v_pk_fma_f32 v[68:69], v[68:69], v[226:227], v[230:231]
	v_cvt_pk_bf16_f32 v70, v70, v71
	v_cvt_pk_bf16_f32 v71, v72, v73
	v_cvt_pk_bf16_f32 v72, v66, v67
	v_cvt_pk_bf16_f32 v73, v68, v69
	s_add_u32 s76, s72, 0xe000
	s_addc_u32 s77, s73, 0
	global_store_dwordx4 v232, v[70:73], s[76:77]
	s_add_u32 s4, s70, 0x1e000
	s_addc_u32 s5, s71, 0
	global_load_dwordx4 v[178:181], v232, s[4:5]
	s_add_u32 s4, s72, 0x1e000
	s_addc_u32 s5, s73, 0
	global_load_dwordx4 v[210:213], v232, s[4:5]
	s_waitcnt vmcnt(21)
	v_lshlrev_b32_e32 v224, 16, v130
	v_and_b32_e32 v225, 0xffff0000, v130
	v_lshlrev_b32_e32 v228, 16, v182
	v_and_b32_e32 v229, 0xffff0000, v182
	v_pk_fma_f32 v[62:63], v[62:63], v[224:225], v[228:229]
	v_lshlrev_b32_e32 v226, 16, v131
	v_and_b32_e32 v227, 0xffff0000, v131
	v_lshlrev_b32_e32 v230, 16, v183
	v_and_b32_e32 v231, 0xffff0000, v183
	v_pk_fma_f32 v[64:65], v[64:65], v[226:227], v[230:231]
	v_lshlrev_b32_e32 v224, 16, v132
	v_and_b32_e32 v225, 0xffff0000, v132
	v_lshlrev_b32_e32 v228, 16, v184
	v_and_b32_e32 v229, 0xffff0000, v184
	v_pk_fma_f32 v[58:59], v[58:59], v[224:225], v[228:229]
	v_lshlrev_b32_e32 v226, 16, v133
	v_and_b32_e32 v227, 0xffff0000, v133
	v_lshlrev_b32_e32 v230, 16, v185
	v_and_b32_e32 v231, 0xffff0000, v185
	v_pk_fma_f32 v[60:61], v[60:61], v[226:227], v[230:231]
	v_cvt_pk_bf16_f32 v62, v62, v63
	v_cvt_pk_bf16_f32 v63, v64, v65
	v_cvt_pk_bf16_f32 v64, v58, v59
	v_cvt_pk_bf16_f32 v65, v60, v61
	s_add_u32 s76, s72, 0x10000
	s_addc_u32 s77, s73, 0
	global_store_dwordx4 v232, v[62:65], s[76:77]
	s_waitcnt vmcnt(19)
	v_lshlrev_b32_e32 v224, 16, v134
	v_and_b32_e32 v225, 0xffff0000, v134
	v_lshlrev_b32_e32 v228, 16, v186
	v_and_b32_e32 v229, 0xffff0000, v186
	v_pk_fma_f32 v[54:55], v[54:55], v[224:225], v[228:229]
	v_lshlrev_b32_e32 v226, 16, v135
	v_and_b32_e32 v227, 0xffff0000, v135
	v_lshlrev_b32_e32 v230, 16, v187
	v_and_b32_e32 v231, 0xffff0000, v187
	v_pk_fma_f32 v[56:57], v[56:57], v[226:227], v[230:231]
	v_lshlrev_b32_e32 v224, 16, v136
	v_and_b32_e32 v225, 0xffff0000, v136
	v_lshlrev_b32_e32 v228, 16, v188
	v_and_b32_e32 v229, 0xffff0000, v188
	v_pk_fma_f32 v[50:51], v[50:51], v[224:225], v[228:229]
	v_lshlrev_b32_e32 v226, 16, v137
	v_and_b32_e32 v227, 0xffff0000, v137
	v_lshlrev_b32_e32 v230, 16, v189
	v_and_b32_e32 v231, 0xffff0000, v189
	v_pk_fma_f32 v[52:53], v[52:53], v[226:227], v[230:231]
	v_cvt_pk_bf16_f32 v54, v54, v55
	v_cvt_pk_bf16_f32 v55, v56, v57
	v_cvt_pk_bf16_f32 v56, v50, v51
	v_cvt_pk_bf16_f32 v57, v52, v53
	s_add_u32 s76, s72, 0x12000
	s_addc_u32 s77, s73, 0
	global_store_dwordx4 v232, v[54:57], s[76:77]
	s_waitcnt vmcnt(17)
	v_lshlrev_b32_e32 v224, 16, v156
	v_and_b32_e32 v225, 0xffff0000, v156
	v_lshlrev_b32_e32 v228, 16, v190
	v_and_b32_e32 v229, 0xffff0000, v190
	v_pk_fma_f32 v[46:47], v[46:47], v[224:225], v[228:229]
	v_lshlrev_b32_e32 v226, 16, v157
	v_and_b32_e32 v227, 0xffff0000, v157
	v_lshlrev_b32_e32 v230, 16, v191
	v_and_b32_e32 v231, 0xffff0000, v191
	v_pk_fma_f32 v[48:49], v[48:49], v[226:227], v[230:231]
	v_lshlrev_b32_e32 v224, 16, v158
	v_and_b32_e32 v225, 0xffff0000, v158
	v_lshlrev_b32_e32 v228, 16, v192
	v_and_b32_e32 v229, 0xffff0000, v192
	v_pk_fma_f32 v[42:43], v[42:43], v[224:225], v[228:229]
	v_lshlrev_b32_e32 v226, 16, v159
	v_and_b32_e32 v227, 0xffff0000, v159
	v_lshlrev_b32_e32 v230, 16, v193
	v_and_b32_e32 v231, 0xffff0000, v193
	v_pk_fma_f32 v[44:45], v[44:45], v[226:227], v[230:231]
	v_cvt_pk_bf16_f32 v46, v46, v47
	v_cvt_pk_bf16_f32 v47, v48, v49
	v_cvt_pk_bf16_f32 v48, v42, v43
	v_cvt_pk_bf16_f32 v49, v44, v45
	s_add_u32 s76, s72, 0x14000
	s_addc_u32 s77, s73, 0
	global_store_dwordx4 v232, v[46:49], s[76:77]
	s_waitcnt vmcnt(15)
	v_lshlrev_b32_e32 v224, 16, v162
	v_and_b32_e32 v225, 0xffff0000, v162
	v_lshlrev_b32_e32 v228, 16, v194
	v_and_b32_e32 v229, 0xffff0000, v194
	v_pk_fma_f32 v[38:39], v[38:39], v[224:225], v[228:229]
	v_lshlrev_b32_e32 v226, 16, v163
	v_and_b32_e32 v227, 0xffff0000, v163
	v_lshlrev_b32_e32 v230, 16, v195
	v_and_b32_e32 v231, 0xffff0000, v195
	v_pk_fma_f32 v[40:41], v[40:41], v[226:227], v[230:231]
	v_lshlrev_b32_e32 v224, 16, v164
	v_and_b32_e32 v225, 0xffff0000, v164
	v_lshlrev_b32_e32 v228, 16, v196
	v_and_b32_e32 v229, 0xffff0000, v196
	v_pk_fma_f32 v[34:35], v[34:35], v[224:225], v[228:229]
	v_lshlrev_b32_e32 v226, 16, v165
	v_and_b32_e32 v227, 0xffff0000, v165
	v_lshlrev_b32_e32 v230, 16, v197
	v_and_b32_e32 v231, 0xffff0000, v197
	v_pk_fma_f32 v[36:37], v[36:37], v[226:227], v[230:231]
	v_cvt_pk_bf16_f32 v38, v38, v39
	v_cvt_pk_bf16_f32 v39, v40, v41
	v_cvt_pk_bf16_f32 v40, v34, v35
	v_cvt_pk_bf16_f32 v41, v36, v37
	s_add_u32 s76, s72, 0x16000
	s_addc_u32 s77, s73, 0
	global_store_dwordx4 v232, v[38:41], s[76:77]
	s_waitcnt vmcnt(13)
	v_lshlrev_b32_e32 v224, 16, v166
	v_and_b32_e32 v225, 0xffff0000, v166
	v_lshlrev_b32_e32 v228, 16, v198
	v_and_b32_e32 v229, 0xffff0000, v198
	v_pk_fma_f32 v[30:31], v[30:31], v[224:225], v[228:229]
	v_lshlrev_b32_e32 v226, 16, v167
	v_and_b32_e32 v227, 0xffff0000, v167
	v_lshlrev_b32_e32 v230, 16, v199
	v_and_b32_e32 v231, 0xffff0000, v199
	v_pk_fma_f32 v[32:33], v[32:33], v[226:227], v[230:231]
	v_lshlrev_b32_e32 v224, 16, v168
	v_and_b32_e32 v225, 0xffff0000, v168
	v_lshlrev_b32_e32 v228, 16, v200
	v_and_b32_e32 v229, 0xffff0000, v200
	v_pk_fma_f32 v[26:27], v[26:27], v[224:225], v[228:229]
	v_lshlrev_b32_e32 v226, 16, v169
	v_and_b32_e32 v227, 0xffff0000, v169
	v_lshlrev_b32_e32 v230, 16, v201
	v_and_b32_e32 v231, 0xffff0000, v201
	v_pk_fma_f32 v[28:29], v[28:29], v[226:227], v[230:231]
	v_cvt_pk_bf16_f32 v30, v30, v31
	v_cvt_pk_bf16_f32 v31, v32, v33
	v_cvt_pk_bf16_f32 v32, v26, v27
	v_cvt_pk_bf16_f32 v33, v28, v29
	s_add_u32 s76, s72, 0x18000
	s_addc_u32 s77, s73, 0
	global_store_dwordx4 v232, v[30:33], s[76:77]
	s_waitcnt vmcnt(11)
	v_lshlrev_b32_e32 v224, 16, v170
	v_and_b32_e32 v225, 0xffff0000, v170
	v_lshlrev_b32_e32 v228, 16, v202
	v_and_b32_e32 v229, 0xffff0000, v202
	v_pk_fma_f32 v[22:23], v[22:23], v[224:225], v[228:229]
	v_lshlrev_b32_e32 v226, 16, v171
	v_and_b32_e32 v227, 0xffff0000, v171
	v_lshlrev_b32_e32 v230, 16, v203
	v_and_b32_e32 v231, 0xffff0000, v203
	v_pk_fma_f32 v[24:25], v[24:25], v[226:227], v[230:231]
	v_lshlrev_b32_e32 v224, 16, v172
	v_and_b32_e32 v225, 0xffff0000, v172
	v_lshlrev_b32_e32 v228, 16, v204
	v_and_b32_e32 v229, 0xffff0000, v204
	v_pk_fma_f32 v[18:19], v[18:19], v[224:225], v[228:229]
	v_lshlrev_b32_e32 v226, 16, v173
	v_and_b32_e32 v227, 0xffff0000, v173
	v_lshlrev_b32_e32 v230, 16, v205
	v_and_b32_e32 v231, 0xffff0000, v205
	v_pk_fma_f32 v[20:21], v[20:21], v[226:227], v[230:231]
	v_cvt_pk_bf16_f32 v22, v22, v23
	v_cvt_pk_bf16_f32 v23, v24, v25
	v_cvt_pk_bf16_f32 v24, v18, v19
	v_cvt_pk_bf16_f32 v25, v20, v21
	s_add_u32 s76, s72, 0x1a000
	s_addc_u32 s77, s73, 0
	global_store_dwordx4 v232, v[22:25], s[76:77]
	s_waitcnt vmcnt(9)
	v_lshlrev_b32_e32 v224, 16, v174
	v_and_b32_e32 v225, 0xffff0000, v174
	v_lshlrev_b32_e32 v228, 16, v206
	v_and_b32_e32 v229, 0xffff0000, v206
	v_pk_fma_f32 v[14:15], v[14:15], v[224:225], v[228:229]
	v_lshlrev_b32_e32 v226, 16, v175
	v_and_b32_e32 v227, 0xffff0000, v175
	v_lshlrev_b32_e32 v230, 16, v207
	v_and_b32_e32 v231, 0xffff0000, v207
	v_pk_fma_f32 v[16:17], v[16:17], v[226:227], v[230:231]
	v_lshlrev_b32_e32 v224, 16, v176
	v_and_b32_e32 v225, 0xffff0000, v176
	v_lshlrev_b32_e32 v228, 16, v208
	v_and_b32_e32 v229, 0xffff0000, v208
	v_pk_fma_f32 v[10:11], v[10:11], v[224:225], v[228:229]
	v_lshlrev_b32_e32 v226, 16, v177
	v_and_b32_e32 v227, 0xffff0000, v177
	v_lshlrev_b32_e32 v230, 16, v209
	v_and_b32_e32 v231, 0xffff0000, v209
	v_pk_fma_f32 v[12:13], v[12:13], v[226:227], v[230:231]
	v_cvt_pk_bf16_f32 v14, v14, v15
	v_cvt_pk_bf16_f32 v15, v16, v17
	v_cvt_pk_bf16_f32 v16, v10, v11
	v_cvt_pk_bf16_f32 v17, v12, v13
	s_add_u32 s76, s72, 0x1c000
	s_addc_u32 s77, s73, 0
	global_store_dwordx4 v232, v[14:17], s[76:77]
	s_waitcnt vmcnt(7)
	v_lshlrev_b32_e32 v224, 16, v178
	v_and_b32_e32 v225, 0xffff0000, v178
	v_lshlrev_b32_e32 v228, 16, v210
	v_and_b32_e32 v229, 0xffff0000, v210
	v_pk_fma_f32 v[6:7], v[6:7], v[224:225], v[228:229]
	v_lshlrev_b32_e32 v226, 16, v179
	v_and_b32_e32 v227, 0xffff0000, v179
	v_lshlrev_b32_e32 v230, 16, v211
	v_and_b32_e32 v231, 0xffff0000, v211
	v_pk_fma_f32 v[8:9], v[8:9], v[226:227], v[230:231]
	v_lshlrev_b32_e32 v224, 16, v180
	v_and_b32_e32 v225, 0xffff0000, v180
	v_lshlrev_b32_e32 v228, 16, v212
	v_and_b32_e32 v229, 0xffff0000, v212
	v_pk_fma_f32 v[0:1], v[0:1], v[224:225], v[228:229]
	v_lshlrev_b32_e32 v226, 16, v181
	v_and_b32_e32 v227, 0xffff0000, v181
	v_lshlrev_b32_e32 v230, 16, v213
	v_and_b32_e32 v231, 0xffff0000, v213
	v_pk_fma_f32 v[2:3], v[2:3], v[226:227], v[230:231]
	v_cvt_pk_bf16_f32 v6, v6, v7
	v_cvt_pk_bf16_f32 v7, v8, v9
	v_cvt_pk_bf16_f32 v8, v0, v1
	v_cvt_pk_bf16_f32 v9, v2, v3
	s_add_u32 s76, s72, 0x1e000
	s_addc_u32 s77, s73, 0
	global_store_dwordx4 v232, v[6:9], s[76:77]
	s_branch .Lmrg_done
.Lmrg_seg2:
	s_add_u32 s70, s26, s93
	s_addc_u32 s71, s27, 0
	s_add_u32 s70, s70, s4
	s_addc_u32 s71, s71, 0
	s_lshl_b32 s5, s8, 19
	s_lshl_b32 s76, s6, 9
	s_add_u32 s5, s5, s76
	s_add_u32 s74, s24, s5
	s_addc_u32 s75, s25, 0
	v_add_u32_e32 v233, s45, v5
	v_lshlrev_b32_e32 v233, 11, v233
	v_lshl_add_u32 v234, v139, 3, s51
	v_lshl_add_u32 v233, v234, 1, v233
	s_add_u32 s4, s70, 0x0
	s_addc_u32 s5, s71, 0
	global_load_dwordx4 v[130:133], v232, s[4:5]
	s_add_u32 s4, s72, 0x0
	s_addc_u32 s5, s73, 0
	global_load_dwordx4 v[182:185], v232, s[4:5]
	s_add_u32 s4, s70, 0x2000
	s_addc_u32 s5, s71, 0
	global_load_dwordx4 v[134:137], v232, s[4:5]
	s_add_u32 s4, s72, 0x2000
	s_addc_u32 s5, s73, 0
	global_load_dwordx4 v[186:189], v232, s[4:5]
	s_add_u32 s4, s70, 0x4000
	s_addc_u32 s5, s71, 0
	global_load_dwordx4 v[156:159], v232, s[4:5]
	s_add_u32 s4, s72, 0x4000
	s_addc_u32 s5, s73, 0
	global_load_dwordx4 v[190:193], v232, s[4:5]
	s_add_u32 s4, s70, 0x6000
	s_addc_u32 s5, s71, 0
	global_load_dwordx4 v[162:165], v232, s[4:5]
	s_add_u32 s4, s72, 0x6000
	s_addc_u32 s5, s73, 0
	global_load_dwordx4 v[194:197], v232, s[4:5]
	s_add_u32 s4, s70, 0x8000
	s_addc_u32 s5, s71, 0
	global_load_dwordx4 v[166:169], v232, s[4:5]
	s_add_u32 s4, s72, 0x8000
	s_addc_u32 s5, s73, 0
	global_load_dwordx4 v[198:201], v232, s[4:5]
	s_add_u32 s4, s70, 0xa000
	s_addc_u32 s5, s71, 0
	global_load_dwordx4 v[170:173], v232, s[4:5]
	s_add_u32 s4, s72, 0xa000
	s_addc_u32 s5, s73, 0
	global_load_dwordx4 v[202:205], v232, s[4:5]
	s_add_u32 s4, s70, 0xc000
	s_addc_u32 s5, s71, 0
	global_load_dwordx4 v[174:177], v232, s[4:5]
	s_add_u32 s4, s72, 0xc000
	s_addc_u32 s5, s73, 0
	global_load_dwordx4 v[206:209], v232, s[4:5]
	s_add_u32 s4, s70, 0xe000
	s_addc_u32 s5, s71, 0
	global_load_dwordx4 v[178:181], v232, s[4:5]
	s_add_u32 s4, s72, 0xe000
	s_addc_u32 s5, s73, 0
	global_load_dwordx4 v[210:213], v232, s[4:5]
	s_waitcnt vmcnt(14)
	v_lshlrev_b32_e32 v224, 16, v130
	v_and_b32_e32 v225, 0xffff0000, v130
	v_lshlrev_b32_e32 v228, 16, v182
	v_and_b32_e32 v229, 0xffff0000, v182
	v_pk_fma_f32 v[126:127], v[126:127], v[224:225], v[228:229]
	v_lshlrev_b32_e32 v226, 16, v131
	v_and_b32_e32 v227, 0xffff0000, v131
	v_lshlrev_b32_e32 v230, 16, v183
	v_and_b32_e32 v231, 0xffff0000, v183
	v_pk_fma_f32 v[128:129], v[128:129], v[226:227], v[230:231]
	v_lshlrev_b32_e32 v224, 16, v132
	v_and_b32_e32 v225, 0xffff0000, v132
	v_lshlrev_b32_e32 v228, 16, v184
	v_and_b32_e32 v229, 0xffff0000, v184
	v_pk_fma_f32 v[122:123], v[122:123], v[224:225], v[228:229]
	v_lshlrev_b32_e32 v226, 16, v133
	v_and_b32_e32 v227, 0xffff0000, v133
	v_lshlrev_b32_e32 v230, 16, v185
	v_and_b32_e32 v231, 0xffff0000, v185
	v_pk_fma_f32 v[124:125], v[124:125], v[226:227], v[230:231]
	v_cvt_pk_bf16_f32 v126, v126, v127
	v_cvt_pk_bf16_f32 v127, v128, v129
	v_cvt_pk_bf16_f32 v128, v122, v123
	v_cvt_pk_bf16_f32 v129, v124, v125
	s_add_u32 s76, s74, 0x0
	s_addc_u32 s77, s75, 0
	global_store_dwordx4 v233, v[126:129], s[76:77]
	s_add_u32 s4, s70, 0x10000
	s_addc_u32 s5, s71, 0
	global_load_dwordx4 v[130:133], v232, s[4:5]
	s_add_u32 s4, s72, 0x10000
	s_addc_u32 s5, s73, 0
	global_load_dwordx4 v[182:185], v232, s[4:5]
	s_waitcnt vmcnt(15)
	v_lshlrev_b32_e32 v224, 16, v134
	v_and_b32_e32 v225, 0xffff0000, v134
	v_lshlrev_b32_e32 v228, 16, v186
	v_and_b32_e32 v229, 0xffff0000, v186
	v_pk_fma_f32 v[118:119], v[118:119], v[224:225], v[228:229]
	v_lshlrev_b32_e32 v226, 16, v135
	v_and_b32_e32 v227, 0xffff0000, v135
	v_lshlrev_b32_e32 v230, 16, v187
	v_and_b32_e32 v231, 0xffff0000, v187
	v_pk_fma_f32 v[120:121], v[120:121], v[226:227], v[230:231]
	v_lshlrev_b32_e32 v224, 16, v136
	v_and_b32_e32 v225, 0xffff0000, v136
	v_lshlrev_b32_e32 v228, 16, v188
	v_and_b32_e32 v229, 0xffff0000, v188
	v_pk_fma_f32 v[114:115], v[114:115], v[224:225], v[228:229]
	v_lshlrev_b32_e32 v226, 16, v137
	v_and_b32_e32 v227, 0xffff0000, v137
	v_lshlrev_b32_e32 v230, 16, v189
	v_and_b32_e32 v231, 0xffff0000, v189
	v_pk_fma_f32 v[116:117], v[116:117], v[226:227], v[230:231]
	v_cvt_pk_bf16_f32 v118, v118, v119
	v_cvt_pk_bf16_f32 v119, v120, v121
	v_cvt_pk_bf16_f32 v120, v114, v115
	v_cvt_pk_bf16_f32 v121, v116, v117
	s_add_u32 s76, s74, 0x8000
	s_addc_u32 s77, s75, 0
	global_store_dwordx4 v233, v[118:121], s[76:77]
	s_add_u32 s4, s70, 0x12000
	s_addc_u32 s5, s71, 0
	global_load_dwordx4 v[134:137], v232, s[4:5]
	s_add_u32 s4, s72, 0x12000
	s_addc_u32 s5, s73, 0
	global_load_dwordx4 v[186:189], v232, s[4:5]
	s_waitcnt vmcnt(16)
	v_lshlrev_b32_e32 v224, 16, v156
	v_and_b32_e32 v225, 0xffff0000, v156
	v_lshlrev_b32_e32 v228, 16, v190
	v_and_b32_e32 v229, 0xffff0000, v190
	v_pk_fma_f32 v[110:111], v[110:111], v[224:225], v[228:229]
	v_lshlrev_b32_e32 v226, 16, v157
	v_and_b32_e32 v227, 0xffff0000, v157
	v_lshlrev_b32_e32 v230, 16, v191
	v_and_b32_e32 v231, 0xffff0000, v191
	v_pk_fma_f32 v[112:113], v[112:113], v[226:227], v[230:231]
	v_lshlrev_b32_e32 v224, 16, v158
	v_and_b32_e32 v225, 0xffff0000, v158
	v_lshlrev_b32_e32 v228, 16, v192
	v_and_b32_e32 v229, 0xffff0000, v192
	v_pk_fma_f32 v[106:107], v[106:107], v[224:225], v[228:229]
	v_lshlrev_b32_e32 v226, 16, v159
	v_and_b32_e32 v227, 0xffff0000, v159
	v_lshlrev_b32_e32 v230, 16, v193
	v_and_b32_e32 v231, 0xffff0000, v193
	v_pk_fma_f32 v[108:109], v[108:109], v[226:227], v[230:231]
	v_cvt_pk_bf16_f32 v110, v110, v111
	v_cvt_pk_bf16_f32 v111, v112, v113
	v_cvt_pk_bf16_f32 v112, v106, v107
	v_cvt_pk_bf16_f32 v113, v108, v109
	s_add_u32 s76, s74, 0x10000
	s_addc_u32 s77, s75, 0
	global_store_dwordx4 v233, v[110:113], s[76:77]
	s_add_u32 s4, s70, 0x14000
	s_addc_u32 s5, s71, 0
	global_load_dwordx4 v[156:159], v232, s[4:5]
	s_add_u32 s4, s72, 0x14000
	s_addc_u32 s5, s73, 0
	global_load_dwordx4 v[190:193], v232, s[4:5]
	s_waitcnt vmcnt(17)
	v_lshlrev_b32_e32 v224, 16, v162
	v_and_b32_e32 v225, 0xffff0000, v162
	v_lshlrev_b32_e32 v228, 16, v194
	v_and_b32_e32 v229, 0xffff0000, v194
	v_pk_fma_f32 v[102:103], v[102:103], v[224:225], v[228:229]
	v_lshlrev_b32_e32 v226, 16, v163
	v_and_b32_e32 v227, 0xffff0000, v163
	v_lshlrev_b32_e32 v230, 16, v195
	v_and_b32_e32 v231, 0xffff0000, v195
	v_pk_fma_f32 v[104:105], v[104:105], v[226:227], v[230:231]
	v_lshlrev_b32_e32 v224, 16, v164
	v_and_b32_e32 v225, 0xffff0000, v164
	v_lshlrev_b32_e32 v228, 16, v196
	v_and_b32_e32 v229, 0xffff0000, v196
	v_pk_fma_f32 v[98:99], v[98:99], v[224:225], v[228:229]
	v_lshlrev_b32_e32 v226, 16, v165
	v_and_b32_e32 v227, 0xffff0000, v165
	v_lshlrev_b32_e32 v230, 16, v197
	v_and_b32_e32 v231, 0xffff0000, v197
	v_pk_fma_f32 v[100:101], v[100:101], v[226:227], v[230:231]
	v_cvt_pk_bf16_f32 v102, v102, v103
	v_cvt_pk_bf16_f32 v103, v104, v105
	v_cvt_pk_bf16_f32 v104, v98, v99
	v_cvt_pk_bf16_f32 v105, v100, v101
	s_add_u32 s76, s74, 0x18000
	s_addc_u32 s77, s75, 0
	global_store_dwordx4 v233, v[102:105], s[76:77]
	s_add_u32 s4, s70, 0x16000
	s_addc_u32 s5, s71, 0
	global_load_dwordx4 v[162:165], v232, s[4:5]
	s_add_u32 s4, s72, 0x16000
	s_addc_u32 s5, s73, 0
	global_load_dwordx4 v[194:197], v232, s[4:5]
	s_waitcnt vmcnt(18)
	v_lshlrev_b32_e32 v224, 16, v166
	v_and_b32_e32 v225, 0xffff0000, v166
	v_lshlrev_b32_e32 v228, 16, v198
	v_and_b32_e32 v229, 0xffff0000, v198
	v_pk_fma_f32 v[94:95], v[94:95], v[224:225], v[228:229]
	v_lshlrev_b32_e32 v226, 16, v167
	v_and_b32_e32 v227, 0xffff0000, v167
	v_lshlrev_b32_e32 v230, 16, v199
	v_and_b32_e32 v231, 0xffff0000, v199
	v_pk_fma_f32 v[96:97], v[96:97], v[226:227], v[230:231]
	v_lshlrev_b32_e32 v224, 16, v168
	v_and_b32_e32 v225, 0xffff0000, v168
	v_lshlrev_b32_e32 v228, 16, v200
	v_and_b32_e32 v229, 0xffff0000, v200
	v_pk_fma_f32 v[90:91], v[90:91], v[224:225], v[228:229]
	v_lshlrev_b32_e32 v226, 16, v169
	v_and_b32_e32 v227, 0xffff0000, v169
	v_lshlrev_b32_e32 v230, 16, v201
	v_and_b32_e32 v231, 0xffff0000, v201
	v_pk_fma_f32 v[92:93], v[92:93], v[226:227], v[230:231]
	v_cvt_pk_bf16_f32 v94, v94, v95
	v_cvt_pk_bf16_f32 v95, v96, v97
	v_cvt_pk_bf16_f32 v96, v90, v91
	v_cvt_pk_bf16_f32 v97, v92, v93
	s_add_u32 s76, s74, 0x40000
	s_addc_u32 s77, s75, 0
	global_store_dwordx4 v233, v[94:97], s[76:77]
	s_add_u32 s4, s70, 0x18000
	s_addc_u32 s5, s71, 0
	global_load_dwordx4 v[166:169], v232, s[4:5]
	s_add_u32 s4, s72, 0x18000
	s_addc_u32 s5, s73, 0
	global_load_dwordx4 v[198:201], v232, s[4:5]
	s_waitcnt vmcnt(19)
	v_lshlrev_b32_e32 v224, 16, v170
	v_and_b32_e32 v225, 0xffff0000, v170
	v_lshlrev_b32_e32 v228, 16, v202
	v_and_b32_e32 v229, 0xffff0000, v202
	v_pk_fma_f32 v[86:87], v[86:87], v[224:225], v[228:229]
	v_lshlrev_b32_e32 v226, 16, v171
	v_and_b32_e32 v227, 0xffff0000, v171
	v_lshlrev_b32_e32 v230, 16, v203
	v_and_b32_e32 v231, 0xffff0000, v203
	v_pk_fma_f32 v[88:89], v[88:89], v[226:227], v[230:231]
	v_lshlrev_b32_e32 v224, 16, v172
	v_and_b32_e32 v225, 0xffff0000, v172
	v_lshlrev_b32_e32 v228, 16, v204
	v_and_b32_e32 v229, 0xffff0000, v204
	v_pk_fma_f32 v[82:83], v[82:83], v[224:225], v[228:229]
	v_lshlrev_b32_e32 v226, 16, v173
	v_and_b32_e32 v227, 0xffff0000, v173
	v_lshlrev_b32_e32 v230, 16, v205
	v_and_b32_e32 v231, 0xffff0000, v205
	v_pk_fma_f32 v[84:85], v[84:85], v[226:227], v[230:231]
	v_cvt_pk_bf16_f32 v86, v86, v87
	v_cvt_pk_bf16_f32 v87, v88, v89
	v_cvt_pk_bf16_f32 v88, v82, v83
	v_cvt_pk_bf16_f32 v89, v84, v85
	s_add_u32 s76, s74, 0x48000
	s_addc_u32 s77, s75, 0
	global_store_dwordx4 v233, v[86:89], s[76:77]
	s_add_u32 s4, s70, 0x1a000
	s_addc_u32 s5, s71, 0
	global_load_dwordx4 v[170:173], v232, s[4:5]
	s_add_u32 s4, s72, 0x1a000
	s_addc_u32 s5, s73, 0
	global_load_dwordx4 v[202:205], v232, s[4:5]
	s_waitcnt vmcnt(20)
	v_lshlrev_b32_e32 v224, 16, v174
	v_and_b32_e32 v225, 0xffff0000, v174
	v_lshlrev_b32_e32 v228, 16, v206
	v_and_b32_e32 v229, 0xffff0000, v206
	v_pk_fma_f32 v[78:79], v[78:79], v[224:225], v[228:229]
	v_lshlrev_b32_e32 v226, 16, v175
	v_and_b32_e32 v227, 0xffff0000, v175
	v_lshlrev_b32_e32 v230, 16, v207
	v_and_b32_e32 v231, 0xffff0000, v207
	v_pk_fma_f32 v[80:81], v[80:81], v[226:227], v[230:231]
	v_lshlrev_b32_e32 v224, 16, v176
	v_and_b32_e32 v225, 0xffff0000, v176
	v_lshlrev_b32_e32 v228, 16, v208
	v_and_b32_e32 v229, 0xffff0000, v208
	v_pk_fma_f32 v[74:75], v[74:75], v[224:225], v[228:229]
	v_lshlrev_b32_e32 v226, 16, v177
	v_and_b32_e32 v227, 0xffff0000, v177
	v_lshlrev_b32_e32 v230, 16, v209
	v_and_b32_e32 v231, 0xffff0000, v209
	v_pk_fma_f32 v[76:77], v[76:77], v[226:227], v[230:231]
	v_cvt_pk_bf16_f32 v78, v78, v79
	v_cvt_pk_bf16_f32 v79, v80, v81
	v_cvt_pk_bf16_f32 v80, v74, v75
	v_cvt_pk_bf16_f32 v81, v76, v77
	s_add_u32 s76, s74, 0x50000
	s_addc_u32 s77, s75, 0
	global_store_dwordx4 v233, v[78:81], s[76:77]
	s_add_u32 s4, s70, 0x1c000
	s_addc_u32 s5, s71, 0
	global_load_dwordx4 v[174:177], v232, s[4:5]
	s_add_u32 s4, s72, 0x1c000
	s_addc_u32 s5, s73, 0
	global_load_dwordx4 v[206:209], v232, s[4:5]
	s_waitcnt vmcnt(21)
	v_lshlrev_b32_e32 v224, 16, v178
	v_and_b32_e32 v225, 0xffff0000, v178
	v_lshlrev_b32_e32 v228, 16, v210
	v_and_b32_e32 v229, 0xffff0000, v210
	v_pk_fma_f32 v[70:71], v[70:71], v[224:225], v[228:229]
	v_lshlrev_b32_e32 v226, 16, v179
	v_and_b32_e32 v227, 0xffff0000, v179
	v_lshlrev_b32_e32 v230, 16, v211
	v_and_b32_e32 v231, 0xffff0000, v211
	v_pk_fma_f32 v[72:73], v[72:73], v[226:227], v[230:231]
	v_lshlrev_b32_e32 v224, 16, v180
	v_and_b32_e32 v225, 0xffff0000, v180
	v_lshlrev_b32_e32 v228, 16, v212
	v_and_b32_e32 v229, 0xffff0000, v212
	v_pk_fma_f32 v[66:67], v[66:67], v[224:225], v[228:229]
	v_lshlrev_b32_e32 v226, 16, v181
	v_and_b32_e32 v227, 0xffff0000, v181
	v_lshlrev_b32_e32 v230, 16, v213
	v_and_b32_e32 v231, 0xffff0000, v213
	v_pk_fma_f32 v[68:69], v[68:69], v[226:227], v[230:231]
	v_cvt_pk_bf16_f32 v70, v70, v71
	v_cvt_pk_bf16_f32 v71, v72, v73
	v_cvt_pk_bf16_f32 v72, v66, v67
	v_cvt_pk_bf16_f32 v73, v68, v69
	s_add_u32 s76, s74, 0x58000
	s_addc_u32 s77, s75, 0
	global_store_dwordx4 v233, v[70:73], s[76:77]
	s_add_u32 s4, s70, 0x1e000
	s_addc_u32 s5, s71, 0
	global_load_dwordx4 v[178:181], v232, s[4:5]
	s_add_u32 s4, s72, 0x1e000
	s_addc_u32 s5, s73, 0
	global_load_dwordx4 v[210:213], v232, s[4:5]
	s_waitcnt vmcnt(21)
	v_lshlrev_b32_e32 v224, 16, v130
	v_and_b32_e32 v225, 0xffff0000, v130
	v_lshlrev_b32_e32 v228, 16, v182
	v_and_b32_e32 v229, 0xffff0000, v182
	v_pk_fma_f32 v[62:63], v[62:63], v[224:225], v[228:229]
	v_lshlrev_b32_e32 v226, 16, v131
	v_and_b32_e32 v227, 0xffff0000, v131
	v_lshlrev_b32_e32 v230, 16, v183
	v_and_b32_e32 v231, 0xffff0000, v183
	v_pk_fma_f32 v[64:65], v[64:65], v[226:227], v[230:231]
	v_lshlrev_b32_e32 v224, 16, v132
	v_and_b32_e32 v225, 0xffff0000, v132
	v_lshlrev_b32_e32 v228, 16, v184
	v_and_b32_e32 v229, 0xffff0000, v184
	v_pk_fma_f32 v[58:59], v[58:59], v[224:225], v[228:229]
	v_lshlrev_b32_e32 v226, 16, v133
	v_and_b32_e32 v227, 0xffff0000, v133
	v_lshlrev_b32_e32 v230, 16, v185
	v_and_b32_e32 v231, 0xffff0000, v185
	v_pk_fma_f32 v[60:61], v[60:61], v[226:227], v[230:231]
	v_cvt_pk_bf16_f32 v62, v62, v63
	v_cvt_pk_bf16_f32 v63, v64, v65
	v_cvt_pk_bf16_f32 v64, v58, v59
	v_cvt_pk_bf16_f32 v65, v60, v61
	s_add_u32 s76, s74, 0x100
	s_addc_u32 s77, s75, 0
	global_store_dwordx4 v233, v[62:65], s[76:77]
	s_waitcnt vmcnt(19)
	v_lshlrev_b32_e32 v224, 16, v134
	v_and_b32_e32 v225, 0xffff0000, v134
	v_lshlrev_b32_e32 v228, 16, v186
	v_and_b32_e32 v229, 0xffff0000, v186
	v_pk_fma_f32 v[54:55], v[54:55], v[224:225], v[228:229]
	v_lshlrev_b32_e32 v226, 16, v135
	v_and_b32_e32 v227, 0xffff0000, v135
	v_lshlrev_b32_e32 v230, 16, v187
	v_and_b32_e32 v231, 0xffff0000, v187
	v_pk_fma_f32 v[56:57], v[56:57], v[226:227], v[230:231]
	v_lshlrev_b32_e32 v224, 16, v136
	v_and_b32_e32 v225, 0xffff0000, v136
	v_lshlrev_b32_e32 v228, 16, v188
	v_and_b32_e32 v229, 0xffff0000, v188
	v_pk_fma_f32 v[50:51], v[50:51], v[224:225], v[228:229]
	v_lshlrev_b32_e32 v226, 16, v137
	v_and_b32_e32 v227, 0xffff0000, v137
	v_lshlrev_b32_e32 v230, 16, v189
	v_and_b32_e32 v231, 0xffff0000, v189
	v_pk_fma_f32 v[52:53], v[52:53], v[226:227], v[230:231]
	v_cvt_pk_bf16_f32 v54, v54, v55
	v_cvt_pk_bf16_f32 v55, v56, v57
	v_cvt_pk_bf16_f32 v56, v50, v51
	v_cvt_pk_bf16_f32 v57, v52, v53
	s_add_u32 s76, s74, 0x8100
	s_addc_u32 s77, s75, 0
	global_store_dwordx4 v233, v[54:57], s[76:77]
	s_waitcnt vmcnt(17)
	v_lshlrev_b32_e32 v224, 16, v156
	v_and_b32_e32 v225, 0xffff0000, v156
	v_lshlrev_b32_e32 v228, 16, v190
	v_and_b32_e32 v229, 0xffff0000, v190
	v_pk_fma_f32 v[46:47], v[46:47], v[224:225], v[228:229]
	v_lshlrev_b32_e32 v226, 16, v157
	v_and_b32_e32 v227, 0xffff0000, v157
	v_lshlrev_b32_e32 v230, 16, v191
	v_and_b32_e32 v231, 0xffff0000, v191
	v_pk_fma_f32 v[48:49], v[48:49], v[226:227], v[230:231]
	v_lshlrev_b32_e32 v224, 16, v158
	v_and_b32_e32 v225, 0xffff0000, v158
	v_lshlrev_b32_e32 v228, 16, v192
	v_and_b32_e32 v229, 0xffff0000, v192
	v_pk_fma_f32 v[42:43], v[42:43], v[224:225], v[228:229]
	v_lshlrev_b32_e32 v226, 16, v159
	v_and_b32_e32 v227, 0xffff0000, v159
	v_lshlrev_b32_e32 v230, 16, v193
	v_and_b32_e32 v231, 0xffff0000, v193
	v_pk_fma_f32 v[44:45], v[44:45], v[226:227], v[230:231]
	v_cvt_pk_bf16_f32 v46, v46, v47
	v_cvt_pk_bf16_f32 v47, v48, v49
	v_cvt_pk_bf16_f32 v48, v42, v43
	v_cvt_pk_bf16_f32 v49, v44, v45
	s_add_u32 s76, s74, 0x10100
	s_addc_u32 s77, s75, 0
	global_store_dwordx4 v233, v[46:49], s[76:77]
	s_waitcnt vmcnt(15)
	v_lshlrev_b32_e32 v224, 16, v162
	v_and_b32_e32 v225, 0xffff0000, v162
	v_lshlrev_b32_e32 v228, 16, v194
	v_and_b32_e32 v229, 0xffff0000, v194
	v_pk_fma_f32 v[38:39], v[38:39], v[224:225], v[228:229]
	v_lshlrev_b32_e32 v226, 16, v163
	v_and_b32_e32 v227, 0xffff0000, v163
	v_lshlrev_b32_e32 v230, 16, v195
	v_and_b32_e32 v231, 0xffff0000, v195
	v_pk_fma_f32 v[40:41], v[40:41], v[226:227], v[230:231]
	v_lshlrev_b32_e32 v224, 16, v164
	v_and_b32_e32 v225, 0xffff0000, v164
	v_lshlrev_b32_e32 v228, 16, v196
	v_and_b32_e32 v229, 0xffff0000, v196
	v_pk_fma_f32 v[34:35], v[34:35], v[224:225], v[228:229]
	v_lshlrev_b32_e32 v226, 16, v165
	v_and_b32_e32 v227, 0xffff0000, v165
	v_lshlrev_b32_e32 v230, 16, v197
	v_and_b32_e32 v231, 0xffff0000, v197
	v_pk_fma_f32 v[36:37], v[36:37], v[226:227], v[230:231]
	v_cvt_pk_bf16_f32 v38, v38, v39
	v_cvt_pk_bf16_f32 v39, v40, v41
	v_cvt_pk_bf16_f32 v40, v34, v35
	v_cvt_pk_bf16_f32 v41, v36, v37
	s_add_u32 s76, s74, 0x18100
	s_addc_u32 s77, s75, 0
	global_store_dwordx4 v233, v[38:41], s[76:77]
	s_waitcnt vmcnt(13)
	v_lshlrev_b32_e32 v224, 16, v166
	v_and_b32_e32 v225, 0xffff0000, v166
	v_lshlrev_b32_e32 v228, 16, v198
	v_and_b32_e32 v229, 0xffff0000, v198
	v_pk_fma_f32 v[30:31], v[30:31], v[224:225], v[228:229]
	v_lshlrev_b32_e32 v226, 16, v167
	v_and_b32_e32 v227, 0xffff0000, v167
	v_lshlrev_b32_e32 v230, 16, v199
	v_and_b32_e32 v231, 0xffff0000, v199
	v_pk_fma_f32 v[32:33], v[32:33], v[226:227], v[230:231]
	v_lshlrev_b32_e32 v224, 16, v168
	v_and_b32_e32 v225, 0xffff0000, v168
	v_lshlrev_b32_e32 v228, 16, v200
	v_and_b32_e32 v229, 0xffff0000, v200
	v_pk_fma_f32 v[26:27], v[26:27], v[224:225], v[228:229]
	v_lshlrev_b32_e32 v226, 16, v169
	v_and_b32_e32 v227, 0xffff0000, v169
	v_lshlrev_b32_e32 v230, 16, v201
	v_and_b32_e32 v231, 0xffff0000, v201
	v_pk_fma_f32 v[28:29], v[28:29], v[226:227], v[230:231]
	v_cvt_pk_bf16_f32 v30, v30, v31
	v_cvt_pk_bf16_f32 v31, v32, v33
	v_cvt_pk_bf16_f32 v32, v26, v27
	v_cvt_pk_bf16_f32 v33, v28, v29
	s_add_u32 s76, s74, 0x40100
	s_addc_u32 s77, s75, 0
	global_store_dwordx4 v233, v[30:33], s[76:77]
	s_waitcnt vmcnt(11)
	v_lshlrev_b32_e32 v224, 16, v170
	v_and_b32_e32 v225, 0xffff0000, v170
	v_lshlrev_b32_e32 v228, 16, v202
	v_and_b32_e32 v229, 0xffff0000, v202
	v_pk_fma_f32 v[22:23], v[22:23], v[224:225], v[228:229]
	v_lshlrev_b32_e32 v226, 16, v171
	v_and_b32_e32 v227, 0xffff0000, v171
	v_lshlrev_b32_e32 v230, 16, v203
	v_and_b32_e32 v231, 0xffff0000, v203
	v_pk_fma_f32 v[24:25], v[24:25], v[226:227], v[230:231]
	v_lshlrev_b32_e32 v224, 16, v172
	v_and_b32_e32 v225, 0xffff0000, v172
	v_lshlrev_b32_e32 v228, 16, v204
	v_and_b32_e32 v229, 0xffff0000, v204
	v_pk_fma_f32 v[18:19], v[18:19], v[224:225], v[228:229]
	v_lshlrev_b32_e32 v226, 16, v173
	v_and_b32_e32 v227, 0xffff0000, v173
	v_lshlrev_b32_e32 v230, 16, v205
	v_and_b32_e32 v231, 0xffff0000, v205
	v_pk_fma_f32 v[20:21], v[20:21], v[226:227], v[230:231]
	v_cvt_pk_bf16_f32 v22, v22, v23
	v_cvt_pk_bf16_f32 v23, v24, v25
	v_cvt_pk_bf16_f32 v24, v18, v19
	v_cvt_pk_bf16_f32 v25, v20, v21
	s_add_u32 s76, s74, 0x48100
	s_addc_u32 s77, s75, 0
	global_store_dwordx4 v233, v[22:25], s[76:77]
	s_waitcnt vmcnt(9)
	v_lshlrev_b32_e32 v224, 16, v174
	v_and_b32_e32 v225, 0xffff0000, v174
	v_lshlrev_b32_e32 v228, 16, v206
	v_and_b32_e32 v229, 0xffff0000, v206
	v_pk_fma_f32 v[14:15], v[14:15], v[224:225], v[228:229]
	v_lshlrev_b32_e32 v226, 16, v175
	v_and_b32_e32 v227, 0xffff0000, v175
	v_lshlrev_b32_e32 v230, 16, v207
	v_and_b32_e32 v231, 0xffff0000, v207
	v_pk_fma_f32 v[16:17], v[16:17], v[226:227], v[230:231]
	v_lshlrev_b32_e32 v224, 16, v176
	v_and_b32_e32 v225, 0xffff0000, v176
	v_lshlrev_b32_e32 v228, 16, v208
	v_and_b32_e32 v229, 0xffff0000, v208
	v_pk_fma_f32 v[10:11], v[10:11], v[224:225], v[228:229]
	v_lshlrev_b32_e32 v226, 16, v177
	v_and_b32_e32 v227, 0xffff0000, v177
	v_lshlrev_b32_e32 v230, 16, v209
	v_and_b32_e32 v231, 0xffff0000, v209
	v_pk_fma_f32 v[12:13], v[12:13], v[226:227], v[230:231]
	v_cvt_pk_bf16_f32 v14, v14, v15
	v_cvt_pk_bf16_f32 v15, v16, v17
	v_cvt_pk_bf16_f32 v16, v10, v11
	v_cvt_pk_bf16_f32 v17, v12, v13
	s_add_u32 s76, s74, 0x50100
	s_addc_u32 s77, s75, 0
	global_store_dwordx4 v233, v[14:17], s[76:77]
	s_waitcnt vmcnt(7)
	v_lshlrev_b32_e32 v224, 16, v178
	v_and_b32_e32 v225, 0xffff0000, v178
	v_lshlrev_b32_e32 v228, 16, v210
	v_and_b32_e32 v229, 0xffff0000, v210
	v_pk_fma_f32 v[6:7], v[6:7], v[224:225], v[228:229]
	v_lshlrev_b32_e32 v226, 16, v179
	v_and_b32_e32 v227, 0xffff0000, v179
	v_lshlrev_b32_e32 v230, 16, v211
	v_and_b32_e32 v231, 0xffff0000, v211
	v_pk_fma_f32 v[8:9], v[8:9], v[226:227], v[230:231]
	v_lshlrev_b32_e32 v224, 16, v180
	v_and_b32_e32 v225, 0xffff0000, v180
	v_lshlrev_b32_e32 v228, 16, v212
	v_and_b32_e32 v229, 0xffff0000, v212
	v_pk_fma_f32 v[0:1], v[0:1], v[224:225], v[228:229]
	v_lshlrev_b32_e32 v226, 16, v181
	v_and_b32_e32 v227, 0xffff0000, v181
	v_lshlrev_b32_e32 v230, 16, v213
	v_and_b32_e32 v231, 0xffff0000, v213
	v_pk_fma_f32 v[2:3], v[2:3], v[226:227], v[230:231]
	v_cvt_pk_bf16_f32 v6, v6, v7
	v_cvt_pk_bf16_f32 v7, v8, v9
	v_cvt_pk_bf16_f32 v8, v0, v1
	v_cvt_pk_bf16_f32 v9, v2, v3
	s_add_u32 s76, s74, 0x58100
	s_addc_u32 s77, s75, 0
	global_store_dwordx4 v233, v[6:9], s[76:77]
.Lmrg_done:
	s_cmp_eq_u32 s65, 2
	s_mov_b64 s[4:5], -1
	s_cbranch_scc1 .LBB0_1268
.LBB0_1439:
	s_lshr_b32 s4, s61, 6
	s_cmp_eq_u32 s61, 0
	s_cselect_b32 s50, s50, s4
	s_andn2_b64 vcc, exec, s[12:13]
	s_cbranch_vccnz .LBB0_1267
	s_barrier
	s_branch .LBB0_1267
